# scan loop on a six-slot LDS-DMA ring (2560 B static LDS), pieces issued five steps ahead
# speedup vs baseline: 1.0024x; 1.0024x over previous
.LBB0_1501:
	s_cmpk_gt_u32 s57, 0xbf
	s_cselect_b64 s[22:23], -1, 0
	s_and_b32 s8, s90, 56
	s_cmp_lg_u32 s8, 0
	s_cselect_b64 s[10:11], -1, 0
	s_bitcmp1_b32 s90, 6
	v_cndmask_b32_e64 v42, 0, 1, s[10:11]
	s_cselect_b64 s[24:25], -1, 0
	v_cmp_eq_u32_e64 s[8:9], 0, v50
	v_add_u32_e32 v160, v160, v158
	s_mov_b32 s35, 5
	s_movk_i32 s36, 0xfe
	v_cmp_ne_u32_e64 s[10:11], 1, v42
	s_movk_i32 s37, 0x1800
	v_mov_b32_e32 v182, 0x27020
	ds_read_b64 v[184:185], v182
	s_waitcnt lgkmcnt(0)
	s_branch .LBB0_1504
.LBB0_1504:
	s_and_b64 vcc, exec, s[22:23]
	s_cbranch_vccz .Lsc_wlo
	s_waitcnt vmcnt(20)
	s_branch .Lsc_wdone
.Lsc_wlo:
	s_waitcnt vmcnt(24)
.Lsc_wdone:
	s_barrier
	s_cmp_eq_u32 s35, 5
	s_cbranch_scc0 .Lsc_nopre
	s_andn2_b64 vcc, exec, s[16:17]
	s_mov_b32 s28, s36
	s_cbranch_vccz .Lsc_pre_cn
	s_mov_b32 s28, 1
.Lsc_pre_cn:
	s_mov_b32 s29, 4
	s_add_i32 s26, s28, s31
	s_mulk_i32 s29, 0x6a00
	s_ashr_i32 s27, s26, 31
	s_add_i32 s38, s29, 0
	s_lshl_b64 s[40:41], s[26:27], 14
	s_add_i32 s29, s38, s30
	v_lshl_add_u64 v[42:43], v[142:143], 0, s[40:41]
	s_mov_b32 m0, s29
	s_and_b64 vcc, exec, s[0:1]
	global_load_lds_dwordx4 v[42:43], off
	v_lshl_add_u64 v[42:43], v[144:145], 0, s[40:41]
	s_add_i32 s40, s28, s34
	s_ashr_i32 s41, s40, 31
	s_add_i32 m0, s29, 0x2000
	s_lshl_b64 s[40:41], s[40:41], 15
	global_load_lds_dwordx4 v[42:43], off
	v_lshl_add_u64 v[42:43], v[146:147], 0, s[40:41]
	s_add_i32 m0, s29, 0x4000
	s_nop 0
	global_load_lds_dwordx4 v[42:43], off
	s_cbranch_vccnz .Lsc_pre_a
	s_lshl_b64 s[40:41], s[26:27], 11
	v_lshl_add_u64 v[42:43], v[148:149], 0, s[40:41]
	s_add_i32 m0, s29, 0x6000
	s_nop 0
	global_load_lds_dwordx4 v[42:43], off

.Lsc_nopre:
	s_andn2_b64 vcc, exec, s[16:17]
	s_cbranch_vccnz .Lsc_dir0
	s_add_i32 s28, s36, -1
	s_cmpk_lt_u32 s35, 0x103
	s_cselect_b32 s28, s28, 0
	s_branch .Lsc_cn_done
.Lsc_dir0:
	s_min_u32 s26, s35, 0x102
	s_add_i32 s28, s26, -3
.Lsc_cn_done:
	s_and_b32 s38, s35, 0xffff
	s_mul_i32 s38, s38, 0xaaab
	s_lshr_b32 s38, s38, 18
	s_mul_i32 s38, s38, 6
	s_sub_i32 s29, s35, s38
	s_add_i32 s26, s28, s31
	s_mulk_i32 s29, 0x6a00
	s_ashr_i32 s27, s26, 31
	s_add_i32 s38, s29, 0
	s_lshl_b64 s[40:41], s[26:27], 14
	s_add_i32 s29, s38, s30
	v_lshl_add_u64 v[42:43], v[142:143], 0, s[40:41]
	s_mov_b32 m0, s29
	s_and_b64 vcc, exec, s[0:1]
	global_load_lds_dwordx4 v[42:43], off
	v_lshl_add_u64 v[42:43], v[144:145], 0, s[40:41]
	s_add_i32 s40, s28, s34
	s_ashr_i32 s41, s40, 31
	s_add_i32 m0, s29, 0x2000
	s_lshl_b64 s[40:41], s[40:41], 15
	global_load_lds_dwordx4 v[42:43], off
	v_lshl_add_u64 v[42:43], v[146:147], 0, s[40:41]
	s_add_i32 m0, s29, 0x4000
	s_nop 0
	global_load_lds_dwordx4 v[42:43], off
	s_cbranch_vccnz .LBB0_1525
	s_lshl_b64 s[40:41], s[26:27], 11
	v_lshl_add_u64 v[42:43], v[148:149], 0, s[40:41]
	s_add_i32 m0, s29, 0x6000
	s_nop 0
	global_load_lds_dwordx4 v[42:43], off

.LBB0_1527:
	s_or_b64 exec, exec, s[28:29]
	s_add_i32 s27, s35, 1
	s_and_b32 s26, 0xffff, s27
	s_mul_i32 s26, s26, 0xaaab
	s_lshr_b32 s26, s26, 18
	s_mul_i32 s26, s26, 6
	s_sub_i32 s26, s27, s26
	s_mulk_i32 s26, 0x6a00
	v_add_u32_e32 v46, s26, v157
	v_add_u32_e32 v42, s26, v159
	v_add_u32_e32 v47, v46, v167
	ds_read_b128 v[42:45], v42 offset:16384
	ds_read_b128 v[134:137], v47
	v_add_u32_e32 v48, v46, v166
	ds_read_b128 v[138:141], v47 offset:4096
	ds_read_b128 v[126:129], v48
	v_add_u32_e32 v47, v46, v168
	ds_read_b128 v[130:133], v48 offset:4096
	ds_read_b128 v[118:121], v47
	v_add_u32_e32 v46, v46, v169
	ds_read_b128 v[122:125], v47 offset:4096
	ds_read_b128 v[114:117], v46
	ds_read_b128 v[110:113], v46 offset:4096
	s_and_b64 vcc, exec, s[12:13]
	s_cbranch_vccnz .LBB0_1531
	v_add_u32_e32 v6, s26, v160
	ds_read_b128 v[2:5], v6 offset:24576
	ds_read_b128 v[6:9], v6 offset:25600

.LBB0_1535:
	s_waitcnt vmcnt(0) lgkmcnt(0)
	s_barrier
	ds_write_b64 v182, v[184:185]
	s_waitcnt lgkmcnt(0)

	.amdhsa_kernel _ZN2fk3fwdENS_4ArgsE
		.amdhsa_group_segment_fixed_size 2560
		.amdhsa_private_segment_fixed_size 0
		.amdhsa_kernarg_size 472
		.amdhsa_user_sgpr_count 2
		.amdhsa_user_sgpr_dispatch_ptr 0
		.amdhsa_user_sgpr_queue_ptr 0
		.amdhsa_user_sgpr_kernarg_segment_ptr 1
		.amdhsa_user_sgpr_dispatch_id 0
		.amdhsa_user_sgpr_kernarg_preload_length 0
		.amdhsa_user_sgpr_kernarg_preload_offset 0
		.amdhsa_user_sgpr_private_segment_size 0
		.amdhsa_uses_dynamic_stack 0
		.amdhsa_enable_private_segment 0
		.amdhsa_system_sgpr_workgroup_id_x 1
		.amdhsa_system_sgpr_workgroup_id_y 0
		.amdhsa_system_sgpr_workgroup_id_z 0
		.amdhsa_system_sgpr_workgroup_info 0
		.amdhsa_system_vgpr_workitem_id 0
		.amdhsa_next_free_vgpr 256
		.amdhsa_next_free_sgpr 102
		.amdhsa_accum_offset 256
		.amdhsa_reserve_vcc 1
		.amdhsa_float_round_mode_32 0
		.amdhsa_float_round_mode_16_64 0
		.amdhsa_float_denorm_mode_32 3
		.amdhsa_float_denorm_mode_16_64 3
		.amdhsa_dx10_clamp 1
		.amdhsa_ieee_mode 1
		.amdhsa_fp16_overflow 0
		.amdhsa_tg_split 0
		.amdhsa_exception_fp_ieee_invalid_op 0
		.amdhsa_exception_fp_denorm_src 0
		.amdhsa_exception_fp_ieee_div_zero 0
		.amdhsa_exception_fp_ieee_overflow 0
		.amdhsa_exception_fp_ieee_underflow 0
		.amdhsa_exception_fp_ieee_inexact 0
		.amdhsa_exception_int_div_zero 0
	.end_amdhsa_kernel

amdhsa.kernels:
  - .agpr_count:     0
    .args:
      - .offset:         0
        .size:           216
        .value_kind:     by_value
      - .offset:         216
        .size:           4
        .value_kind:     hidden_block_count_x
      - .offset:         220
        .size:           4
        .value_kind:     hidden_block_count_y
      - .offset:         224
        .size:           4
        .value_kind:     hidden_block_count_z
      - .offset:         228
        .size:           2
        .value_kind:     hidden_group_size_x
      - .offset:         230
        .size:           2
        .value_kind:     hidden_group_size_y
      - .offset:         232
        .size:           2
        .value_kind:     hidden_group_size_z
      - .offset:         234
        .size:           2
        .value_kind:     hidden_remainder_x
      - .offset:         236
        .size:           2
        .value_kind:     hidden_remainder_y
      - .offset:         238
        .size:           2
        .value_kind:     hidden_remainder_z
      - .offset:         256
        .size:           8
        .value_kind:     hidden_global_offset_x
      - .offset:         264
        .size:           8
        .value_kind:     hidden_global_offset_y
      - .offset:         272
        .size:           8
        .value_kind:     hidden_global_offset_z
      - .offset:         280
        .size:           2
        .value_kind:     hidden_grid_dims
      - .offset:         336
        .size:           4
        .value_kind:     hidden_dynamic_lds_size
    .group_segment_fixed_size: 2560
    .kernarg_segment_align: 8
    .kernarg_segment_size: 472
    .language:       OpenCL C
    .language_version:
      - 2
      - 0
    .max_flat_workgroup_size: 512
    .name:           _ZN2fk3fwdENS_4ArgsE
    .private_segment_fixed_size: 0
    .sgpr_count:     108
    .sgpr_spill_count: 43
    .symbol:         _ZN2fk3fwdENS_4ArgsE.kd
    .uniform_work_group_size: 1
    .uses_dynamic_stack: false
    .vgpr_count:     256
    .vgpr_spill_count: 0
    .wavefront_size: 64
